# own phase YB stores write-through (sc1) to leave less dirty L2 data for the barrier write-back; v75 otherwise
# baseline (speedup 1.0000x reference)
.LBB0_925:
	s_waitcnt vmcnt(2)
	v_cndmask_b32_e32 v64, 0, v129, vcc
	v_cndmask_b32_e64 v65, v128, 0, s[86:87]
	v_cndmask_b32_e64 v66, 0, v130, s[38:39]
	v_add_f32_e32 v64, v65, v64
	v_add_f32_e32 v64, v66, v64
	s_waitcnt lgkmcnt(0)
	v_add_f32_e32 v65, v159, v161
	v_add_f32_e32 v64, v64, v65
	v_div_scale_f32 v65, s[38:39], v64, v64, 1.0
	v_rcp_f32_e32 v66, v65
	s_add_u32 s38, s58, s96
	s_addc_u32 s39, s59, 0
	s_add_i32 s86, s62, 1
	v_fma_f32 v67, -v65, v66, 1.0
	v_fmac_f32_e32 v66, v67, v66
	v_div_scale_f32 v67, vcc, 1.0, v64, 1.0
	s_waitcnt vmcnt(0)
	v_mul_f32_e32 v68, v67, v66
	v_fma_f32 v69, -v65, v68, v67
	v_fmac_f32_e32 v68, v69, v66
	v_fma_f32 v65, -v65, v68, v67
	v_div_fmas_f32 v65, v65, v66, v68
	v_div_fixup_f32 v68, v65, v64, 1.0
	v_mul_f32_e32 v48, v68, v48
	v_mul_f32_e32 v49, v68, v49
	v_cvt_pk_bf16_f32 v48, v48, v49
	v_mul_f32_e32 v49, v68, v50
	v_mul_f32_e32 v50, v68, v51
	v_cvt_pk_bf16_f32 v49, v49, v50
	ds_write_b64 v158, v[48:49]
	v_mul_f32_e32 v48, v68, v52
	v_mul_f32_e32 v49, v68, v53
	v_cvt_pk_bf16_f32 v48, v48, v49
	v_mul_f32_e32 v49, v68, v54
	v_mul_f32_e32 v50, v68, v55
	v_cvt_pk_bf16_f32 v49, v49, v50
	ds_write_b64 v158, v[48:49] offset:16
	v_mul_f32_e32 v48, v68, v56
	v_mul_f32_e32 v49, v68, v57
	v_cvt_pk_bf16_f32 v48, v48, v49
	v_mul_f32_e32 v49, v68, v58
	v_mul_f32_e32 v50, v68, v59
	v_cvt_pk_bf16_f32 v49, v49, v50
	ds_write_b64 v158, v[48:49] offset:32
	v_mul_f32_e32 v48, v68, v60
	v_mul_f32_e32 v49, v68, v61
	v_cvt_pk_bf16_f32 v48, v48, v49
	v_mul_f32_e32 v49, v68, v62
	v_mul_f32_e32 v50, v68, v63
	v_cvt_pk_bf16_f32 v49, v49, v50
	ds_write_b64 v158, v[48:49] offset:48
	s_waitcnt lgkmcnt(0)
	ds_read_b128 v[48:51], v157
	ds_read_b128 v[52:55], v160
	v_mov_b32_e32 v65, s39
	v_or_b32_e32 v64, s38, v132
	v_lshlrev_b64 v[64:65], 11, v[64:65]
	v_mov_b32_e32 v67, s39
	v_or_b32_e32 v66, s38, v134
	v_lshlrev_b64 v[56:57], 11, v[66:67]
	v_lshl_add_u64 v[58:59], v[142:143], 0, v[64:65]
	v_lshl_add_u64 v[56:57], v[142:143], 0, v[56:57]
	s_waitcnt lgkmcnt(0)
	global_store_dwordx4 v[58:59], v[52:55], off sc1
	global_store_dwordx4 v[56:57], v[48:51], off sc1
	v_mul_f32_e32 v32, v68, v32
	v_mul_f32_e32 v33, v68, v33
	s_waitcnt lgkmcnt(0)
	v_cvt_pk_bf16_f32 v32, v32, v33
	v_mul_f32_e32 v33, v68, v34
	v_mul_f32_e32 v34, v68, v35
	v_cvt_pk_bf16_f32 v33, v33, v34
	ds_write_b64 v158, v[32:33]
	v_mul_f32_e32 v32, v68, v36
	v_mul_f32_e32 v33, v68, v37
	v_cvt_pk_bf16_f32 v32, v32, v33
	v_mul_f32_e32 v33, v68, v38
	v_mul_f32_e32 v34, v68, v39
	v_cvt_pk_bf16_f32 v33, v33, v34
	ds_write_b64 v158, v[32:33] offset:16
	v_mul_f32_e32 v32, v68, v40
	v_mul_f32_e32 v33, v68, v41
	v_cvt_pk_bf16_f32 v32, v32, v33
	v_mul_f32_e32 v33, v68, v42
	v_mul_f32_e32 v34, v68, v43
	v_cvt_pk_bf16_f32 v33, v33, v34
	ds_write_b64 v158, v[32:33] offset:32
	v_mul_f32_e32 v32, v68, v44
	v_mul_f32_e32 v33, v68, v45
	v_cvt_pk_bf16_f32 v32, v32, v33
	v_mul_f32_e32 v33, v68, v46
	v_mul_f32_e32 v34, v68, v47
	v_cvt_pk_bf16_f32 v33, v33, v34
	ds_write_b64 v158, v[32:33] offset:48
	s_waitcnt lgkmcnt(0)
	ds_read_b128 v[32:35], v160
	ds_read_b128 v[36:39], v157
	s_waitcnt lgkmcnt(1)
	global_store_dwordx4 v[58:59], v[32:35], off offset:64 sc1
	s_waitcnt lgkmcnt(0)
	global_store_dwordx4 v[56:57], v[36:39], off offset:64 sc1
	v_mul_f32_e32 v16, v68, v16
	v_mul_f32_e32 v17, v68, v17
	s_waitcnt lgkmcnt(0)
	v_cvt_pk_bf16_f32 v16, v16, v17
	v_mul_f32_e32 v17, v68, v18
	v_mul_f32_e32 v18, v68, v19
	v_cvt_pk_bf16_f32 v17, v17, v18
	ds_write_b64 v158, v[16:17]
	v_mul_f32_e32 v16, v68, v20
	v_mul_f32_e32 v17, v68, v21
	v_cvt_pk_bf16_f32 v16, v16, v17
	v_mul_f32_e32 v17, v68, v22
	v_mul_f32_e32 v18, v68, v23
	v_cvt_pk_bf16_f32 v17, v17, v18
	ds_write_b64 v158, v[16:17] offset:16
	v_mul_f32_e32 v16, v68, v24
	v_mul_f32_e32 v17, v68, v25
	v_cvt_pk_bf16_f32 v16, v16, v17
	v_mul_f32_e32 v17, v68, v26
	v_mul_f32_e32 v18, v68, v27
	v_cvt_pk_bf16_f32 v17, v17, v18
	ds_write_b64 v158, v[16:17] offset:32
	v_mul_f32_e32 v16, v68, v28
	v_mul_f32_e32 v17, v68, v29
	v_cvt_pk_bf16_f32 v16, v16, v17
	v_mul_f32_e32 v17, v68, v30
	v_mul_f32_e32 v18, v68, v31
	v_cvt_pk_bf16_f32 v17, v17, v18
	ds_write_b64 v158, v[16:17] offset:48
	s_waitcnt lgkmcnt(0)
	ds_read_b128 v[16:19], v160
	ds_read_b128 v[20:23], v157
	s_waitcnt lgkmcnt(1)
	global_store_dwordx4 v[58:59], v[16:19], off offset:128 sc1
	s_waitcnt lgkmcnt(0)
	global_store_dwordx4 v[56:57], v[20:23], off offset:128 sc1
	v_mul_f32_e32 v0, v68, v0
	v_mul_f32_e32 v1, v68, v1
	s_waitcnt lgkmcnt(0)
	v_cvt_pk_bf16_f32 v0, v0, v1
	v_mul_f32_e32 v1, v68, v2
	v_mul_f32_e32 v2, v68, v3
	v_cvt_pk_bf16_f32 v1, v1, v2
	ds_write_b64 v158, v[0:1]
	v_mul_f32_e32 v0, v68, v4
	v_mul_f32_e32 v1, v68, v5
	v_cvt_pk_bf16_f32 v0, v0, v1
	v_mul_f32_e32 v1, v68, v6
	v_mul_f32_e32 v2, v68, v7
	v_cvt_pk_bf16_f32 v1, v1, v2
	ds_write_b64 v158, v[0:1] offset:16
	v_mul_f32_e32 v0, v68, v8
	v_mul_f32_e32 v1, v68, v9
	v_cvt_pk_bf16_f32 v0, v0, v1
	v_mul_f32_e32 v1, v68, v10
	v_mul_f32_e32 v2, v68, v11
	v_cvt_pk_bf16_f32 v1, v1, v2
	ds_write_b64 v158, v[0:1] offset:32
	v_mul_f32_e32 v0, v68, v12
	v_mul_f32_e32 v1, v68, v13
	v_cvt_pk_bf16_f32 v0, v0, v1
	v_mul_f32_e32 v1, v68, v14
	v_mul_f32_e32 v2, v68, v15
	v_cvt_pk_bf16_f32 v1, v1, v2
	ds_write_b64 v158, v[0:1] offset:48
	s_waitcnt lgkmcnt(0)
	ds_read_b128 v[0:3], v160
	ds_read_b128 v[4:7], v157
	s_cmp_lg_u32 s62, 3
	s_cselect_b32 s38, s86, 3
	s_add_i32 s62, s38, s44
	s_ashr_i32 s38, s62, 8
	s_lshl_b32 s87, s62, 8
	s_ashr_i32 s39, s38, 31
	s_and_b32 s87, s87, 0x1f00
	s_waitcnt lgkmcnt(1)
	global_store_dwordx4 v[58:59], v[0:3], off offset:192 sc1
	s_waitcnt lgkmcnt(0)
	global_store_dwordx4 v[56:57], v[4:7], off offset:192 sc1
	s_lshl_b64 s[38:39], s[38:39], 13
	s_add_i32 s87, s87, s64
	s_waitcnt lgkmcnt(0)
	v_mbcnt_lo_u32_b32 v2, -1, 0
	v_mbcnt_hi_u32_b32 v2, -1, v2
	s_add_u32 s38, s38, s87
	v_ashrrev_i32_e32 v0, 2, v2
	v_ashrrev_i32_e32 v1, 31, v0
	s_addc_u32 s39, s39, 0
	v_lshl_add_u64 v[0:1], s[38:39], 0, v[0:1]
	v_lshlrev_b64 v[0:1], 11, v[0:1]
	s_lshl_b32 s38, s62, 3
	v_lshl_add_u64 v[0:1], s[56:57], 0, v[0:1]
	s_and_b32 s62, s38, 0x700
	v_lshlrev_b32_e32 v2, 4, v2
	v_lshl_add_u64 v[0:1], v[0:1], 0, s[62:63]
	v_and_b32_e32 v138, 48, v2
	v_lshl_add_u64 v[16:17], v[0:1], 0, v[138:139]
	v_add_co_u32_e32 v24, vcc, 0x8000, v16
	s_cmp_lg_u32 s86, 4
	s_nop 0
	v_addc_co_u32_e32 v25, vcc, 0, v17, vcc
	global_load_dwordx4 v[0:3], v[16:17], off
	global_load_dwordx4 v[4:7], v[16:17], off offset:64
	global_load_dwordx4 v[20:23], v[24:25], off
	global_load_dwordx4 v[12:15], v[24:25], off offset:64
	global_load_dwordx4 v[8:11], v[16:17], off offset:128
	s_nop 0
	global_load_dwordx4 v[16:19], v[16:17], off offset:192
	s_nop 0
	global_load_dwordx4 v[28:31], v[24:25], off offset:128
	s_nop 0
	global_load_dwordx4 v[24:27], v[24:25], off offset:192
	s_mov_b32 s62, s86
	s_cbranch_scc0 .LBB0_938
